# LRU scans (pass-1 and carry pass) unrolled with double-buffered LDS prefetch instead of read-wait per row pair
# speedup vs baseline: 1.0030x; 1.0030x over previous
.Lscan1_body:
	ds_read2st64_b32 v[66:67], v2 offset1:4
	ds_read2st64_b32 v[68:69], v2 offset0:8 offset1:12
	ds_read2st64_b32 v[70:71], v2 offset0:16 offset1:20
	ds_read2st64_b32 v[72:73], v2 offset0:24 offset1:28
	ds_read2st64_b32 v[74:75], v2 offset0:32 offset1:36
	ds_read2st64_b32 v[76:77], v2 offset0:40 offset1:44
	ds_read2st64_b32 v[78:79], v2 offset0:48 offset1:52
	ds_read2st64_b32 v[80:81], v2 offset0:56 offset1:60
	ds_read2st64_b32 v[82:83], v2 offset0:64 offset1:68
	ds_read2st64_b32 v[84:85], v2 offset0:72 offset1:76
	ds_read2st64_b32 v[86:87], v2 offset0:80 offset1:84
	ds_read2st64_b32 v[88:89], v2 offset0:88 offset1:92
	ds_read2st64_b32 v[90:91], v2 offset0:96 offset1:100
	ds_read2st64_b32 v[92:93], v2 offset0:104 offset1:108
	ds_read2st64_b32 v[94:95], v2 offset0:112 offset1:116
	ds_read2st64_b32 v[96:97], v2 offset0:120 offset1:124
	s_waitcnt lgkmcnt(8)
	v_cvt_f32_f16_e32 v98, v66
	v_cvt_f32_f16_e32 v99, v67
	v_cvt_f32_f16_e32 v100, v68
	v_cvt_f32_f16_e32 v101, v69
	v_cvt_f32_f16_e32 v102, v70
	v_cvt_f32_f16_e32 v103, v71
	v_cvt_f32_f16_e32 v104, v72
	v_cvt_f32_f16_e32 v105, v73
	v_cvt_f32_f16_e32 v106, v74
	v_cvt_f32_f16_e32 v107, v75
	v_cvt_f32_f16_e32 v108, v76
	v_cvt_f32_f16_e32 v109, v77
	v_cvt_f32_f16_e32 v110, v78
	v_cvt_f32_f16_e32 v111, v79
	v_cvt_f32_f16_e32 v112, v80
	v_cvt_f32_f16_e32 v113, v81
	v_exp_f32_e32 v98, v98
	v_exp_f32_e32 v99, v99
	v_exp_f32_e32 v100, v100
	v_exp_f32_e32 v101, v101
	v_exp_f32_e32 v102, v102
	v_exp_f32_e32 v103, v103
	v_exp_f32_e32 v104, v104
	v_exp_f32_e32 v105, v105
	v_exp_f32_e32 v106, v106
	v_exp_f32_e32 v107, v107
	v_exp_f32_e32 v108, v108
	v_exp_f32_e32 v109, v109
	v_exp_f32_e32 v110, v110
	v_exp_f32_e32 v111, v111
	v_exp_f32_e32 v112, v112
	v_exp_f32_e32 v113, v113
	v_and_b32_e32 v66, 0xffff0000, v66
	v_and_b32_e32 v67, 0xffff0000, v67
	v_and_b32_e32 v68, 0xffff0000, v68
	v_and_b32_e32 v69, 0xffff0000, v69
	v_and_b32_e32 v70, 0xffff0000, v70
	v_and_b32_e32 v71, 0xffff0000, v71
	v_and_b32_e32 v72, 0xffff0000, v72
	v_and_b32_e32 v73, 0xffff0000, v73
	v_and_b32_e32 v74, 0xffff0000, v74
	v_and_b32_e32 v75, 0xffff0000, v75
	v_and_b32_e32 v76, 0xffff0000, v76
	v_and_b32_e32 v77, 0xffff0000, v77
	v_and_b32_e32 v78, 0xffff0000, v78
	v_and_b32_e32 v79, 0xffff0000, v79
	v_and_b32_e32 v80, 0xffff0000, v80
	v_and_b32_e32 v81, 0xffff0000, v81
	v_fmac_f32_e32 v66, v1, v98
	v_mul_f32_e32 v0, v0, v98
	v_fmac_f32_e32 v67, v66, v99
	v_mul_f32_e32 v0, v0, v99
	v_fmac_f32_e32 v68, v67, v100
	v_mul_f32_e32 v0, v0, v100
	v_fmac_f32_e32 v69, v68, v101
	v_mul_f32_e32 v0, v0, v101
	v_fmac_f32_e32 v70, v69, v102
	v_mul_f32_e32 v0, v0, v102
	v_fmac_f32_e32 v71, v70, v103
	v_mul_f32_e32 v0, v0, v103
	v_fmac_f32_e32 v72, v71, v104
	v_mul_f32_e32 v0, v0, v104
	v_fmac_f32_e32 v73, v72, v105
	v_mul_f32_e32 v0, v0, v105
	v_fmac_f32_e32 v74, v73, v106
	v_mul_f32_e32 v0, v0, v106
	v_fmac_f32_e32 v75, v74, v107
	v_mul_f32_e32 v0, v0, v107
	v_fmac_f32_e32 v76, v75, v108
	v_mul_f32_e32 v0, v0, v108
	v_fmac_f32_e32 v77, v76, v109
	v_mul_f32_e32 v0, v0, v109
	v_fmac_f32_e32 v78, v77, v110
	v_mul_f32_e32 v0, v0, v110
	v_fmac_f32_e32 v79, v78, v111
	v_mul_f32_e32 v0, v0, v111
	v_fmac_f32_e32 v80, v79, v112
	v_mul_f32_e32 v0, v0, v112
	v_fmac_f32_e32 v81, v80, v113
	v_mul_f32_e32 v0, v0, v113
	v_mov_b32_e32 v1, v81
	ds_read2st64_b32 v[66:67], v2 offset0:128 offset1:132
	ds_read2st64_b32 v[68:69], v2 offset0:136 offset1:140
	ds_read2st64_b32 v[70:71], v2 offset0:144 offset1:148
	ds_read2st64_b32 v[72:73], v2 offset0:152 offset1:156
	ds_read2st64_b32 v[74:75], v2 offset0:160 offset1:164
	ds_read2st64_b32 v[76:77], v2 offset0:168 offset1:172
	ds_read2st64_b32 v[78:79], v2 offset0:176 offset1:180
	ds_read2st64_b32 v[80:81], v2 offset0:184 offset1:188
	s_waitcnt lgkmcnt(8)
	v_cvt_f32_f16_e32 v98, v82
	v_cvt_f32_f16_e32 v99, v83
	v_cvt_f32_f16_e32 v100, v84
	v_cvt_f32_f16_e32 v101, v85
	v_cvt_f32_f16_e32 v102, v86
	v_cvt_f32_f16_e32 v103, v87
	v_cvt_f32_f16_e32 v104, v88
	v_cvt_f32_f16_e32 v105, v89
	v_cvt_f32_f16_e32 v106, v90
	v_cvt_f32_f16_e32 v107, v91
	v_cvt_f32_f16_e32 v108, v92
	v_cvt_f32_f16_e32 v109, v93
	v_cvt_f32_f16_e32 v110, v94
	v_cvt_f32_f16_e32 v111, v95
	v_cvt_f32_f16_e32 v112, v96
	v_cvt_f32_f16_e32 v113, v97
	v_exp_f32_e32 v98, v98
	v_exp_f32_e32 v99, v99
	v_exp_f32_e32 v100, v100
	v_exp_f32_e32 v101, v101
	v_exp_f32_e32 v102, v102
	v_exp_f32_e32 v103, v103
	v_exp_f32_e32 v104, v104
	v_exp_f32_e32 v105, v105
	v_exp_f32_e32 v106, v106
	v_exp_f32_e32 v107, v107
	v_exp_f32_e32 v108, v108
	v_exp_f32_e32 v109, v109
	v_exp_f32_e32 v110, v110
	v_exp_f32_e32 v111, v111
	v_exp_f32_e32 v112, v112
	v_exp_f32_e32 v113, v113
	v_and_b32_e32 v82, 0xffff0000, v82
	v_and_b32_e32 v83, 0xffff0000, v83
	v_and_b32_e32 v84, 0xffff0000, v84
	v_and_b32_e32 v85, 0xffff0000, v85
	v_and_b32_e32 v86, 0xffff0000, v86
	v_and_b32_e32 v87, 0xffff0000, v87
	v_and_b32_e32 v88, 0xffff0000, v88
	v_and_b32_e32 v89, 0xffff0000, v89
	v_and_b32_e32 v90, 0xffff0000, v90
	v_and_b32_e32 v91, 0xffff0000, v91
	v_and_b32_e32 v92, 0xffff0000, v92
	v_and_b32_e32 v93, 0xffff0000, v93
	v_and_b32_e32 v94, 0xffff0000, v94
	v_and_b32_e32 v95, 0xffff0000, v95
	v_and_b32_e32 v96, 0xffff0000, v96
	v_and_b32_e32 v97, 0xffff0000, v97
	v_fmac_f32_e32 v82, v1, v98
	v_mul_f32_e32 v0, v0, v98
	v_fmac_f32_e32 v83, v82, v99
	v_mul_f32_e32 v0, v0, v99
	v_fmac_f32_e32 v84, v83, v100
	v_mul_f32_e32 v0, v0, v100
	v_fmac_f32_e32 v85, v84, v101
	v_mul_f32_e32 v0, v0, v101
	v_fmac_f32_e32 v86, v85, v102
	v_mul_f32_e32 v0, v0, v102
	v_fmac_f32_e32 v87, v86, v103
	v_mul_f32_e32 v0, v0, v103
	v_fmac_f32_e32 v88, v87, v104
	v_mul_f32_e32 v0, v0, v104
	v_fmac_f32_e32 v89, v88, v105
	v_mul_f32_e32 v0, v0, v105
	v_fmac_f32_e32 v90, v89, v106
	v_mul_f32_e32 v0, v0, v106
	v_fmac_f32_e32 v91, v90, v107
	v_mul_f32_e32 v0, v0, v107
	v_fmac_f32_e32 v92, v91, v108
	v_mul_f32_e32 v0, v0, v108
	v_fmac_f32_e32 v93, v92, v109
	v_mul_f32_e32 v0, v0, v109
	v_fmac_f32_e32 v94, v93, v110
	v_mul_f32_e32 v0, v0, v110
	v_fmac_f32_e32 v95, v94, v111
	v_mul_f32_e32 v0, v0, v111
	v_fmac_f32_e32 v96, v95, v112
	v_mul_f32_e32 v0, v0, v112
	v_fmac_f32_e32 v97, v96, v113
	v_mul_f32_e32 v0, v0, v113
	v_mov_b32_e32 v1, v97
	ds_read2st64_b32 v[82:83], v2 offset0:192 offset1:196
	ds_read2st64_b32 v[84:85], v2 offset0:200 offset1:204
	ds_read2st64_b32 v[86:87], v2 offset0:208 offset1:212
	ds_read2st64_b32 v[88:89], v2 offset0:216 offset1:220
	ds_read2st64_b32 v[90:91], v2 offset0:224 offset1:228
	ds_read2st64_b32 v[92:93], v2 offset0:232 offset1:236
	ds_read2st64_b32 v[94:95], v2 offset0:240 offset1:244
	ds_read2st64_b32 v[96:97], v2 offset0:248 offset1:252
	s_waitcnt lgkmcnt(8)
	v_cvt_f32_f16_e32 v98, v66
	v_cvt_f32_f16_e32 v99, v67
	v_cvt_f32_f16_e32 v100, v68
	v_cvt_f32_f16_e32 v101, v69
	v_cvt_f32_f16_e32 v102, v70
	v_cvt_f32_f16_e32 v103, v71
	v_cvt_f32_f16_e32 v104, v72
	v_cvt_f32_f16_e32 v105, v73
	v_cvt_f32_f16_e32 v106, v74
	v_cvt_f32_f16_e32 v107, v75
	v_cvt_f32_f16_e32 v108, v76
	v_cvt_f32_f16_e32 v109, v77
	v_cvt_f32_f16_e32 v110, v78
	v_cvt_f32_f16_e32 v111, v79
	v_cvt_f32_f16_e32 v112, v80
	v_cvt_f32_f16_e32 v113, v81
	v_exp_f32_e32 v98, v98
	v_exp_f32_e32 v99, v99
	v_exp_f32_e32 v100, v100
	v_exp_f32_e32 v101, v101
	v_exp_f32_e32 v102, v102
	v_exp_f32_e32 v103, v103
	v_exp_f32_e32 v104, v104
	v_exp_f32_e32 v105, v105
	v_exp_f32_e32 v106, v106
	v_exp_f32_e32 v107, v107
	v_exp_f32_e32 v108, v108
	v_exp_f32_e32 v109, v109
	v_exp_f32_e32 v110, v110
	v_exp_f32_e32 v111, v111
	v_exp_f32_e32 v112, v112
	v_exp_f32_e32 v113, v113
	v_and_b32_e32 v66, 0xffff0000, v66
	v_and_b32_e32 v67, 0xffff0000, v67
	v_and_b32_e32 v68, 0xffff0000, v68
	v_and_b32_e32 v69, 0xffff0000, v69
	v_and_b32_e32 v70, 0xffff0000, v70
	v_and_b32_e32 v71, 0xffff0000, v71
	v_and_b32_e32 v72, 0xffff0000, v72
	v_and_b32_e32 v73, 0xffff0000, v73
	v_and_b32_e32 v74, 0xffff0000, v74
	v_and_b32_e32 v75, 0xffff0000, v75
	v_and_b32_e32 v76, 0xffff0000, v76
	v_and_b32_e32 v77, 0xffff0000, v77
	v_and_b32_e32 v78, 0xffff0000, v78
	v_and_b32_e32 v79, 0xffff0000, v79
	v_and_b32_e32 v80, 0xffff0000, v80
	v_and_b32_e32 v81, 0xffff0000, v81
	v_fmac_f32_e32 v66, v1, v98
	v_mul_f32_e32 v0, v0, v98
	v_fmac_f32_e32 v67, v66, v99
	v_mul_f32_e32 v0, v0, v99
	v_fmac_f32_e32 v68, v67, v100
	v_mul_f32_e32 v0, v0, v100
	v_fmac_f32_e32 v69, v68, v101
	v_mul_f32_e32 v0, v0, v101
	v_fmac_f32_e32 v70, v69, v102
	v_mul_f32_e32 v0, v0, v102
	v_fmac_f32_e32 v71, v70, v103
	v_mul_f32_e32 v0, v0, v103
	v_fmac_f32_e32 v72, v71, v104
	v_mul_f32_e32 v0, v0, v104
	v_fmac_f32_e32 v73, v72, v105
	v_mul_f32_e32 v0, v0, v105
	v_fmac_f32_e32 v74, v73, v106
	v_mul_f32_e32 v0, v0, v106
	v_fmac_f32_e32 v75, v74, v107
	v_mul_f32_e32 v0, v0, v107
	v_fmac_f32_e32 v76, v75, v108
	v_mul_f32_e32 v0, v0, v108
	v_fmac_f32_e32 v77, v76, v109
	v_mul_f32_e32 v0, v0, v109
	v_fmac_f32_e32 v78, v77, v110
	v_mul_f32_e32 v0, v0, v110
	v_fmac_f32_e32 v79, v78, v111
	v_mul_f32_e32 v0, v0, v111
	v_fmac_f32_e32 v80, v79, v112
	v_mul_f32_e32 v0, v0, v112
	v_fmac_f32_e32 v81, v80, v113
	v_mul_f32_e32 v0, v0, v113
	v_mov_b32_e32 v1, v81
	s_waitcnt lgkmcnt(0)
	v_cvt_f32_f16_e32 v98, v82
	v_cvt_f32_f16_e32 v99, v83
	v_cvt_f32_f16_e32 v100, v84
	v_cvt_f32_f16_e32 v101, v85
	v_cvt_f32_f16_e32 v102, v86
	v_cvt_f32_f16_e32 v103, v87
	v_cvt_f32_f16_e32 v104, v88
	v_cvt_f32_f16_e32 v105, v89
	v_cvt_f32_f16_e32 v106, v90
	v_cvt_f32_f16_e32 v107, v91
	v_cvt_f32_f16_e32 v108, v92
	v_cvt_f32_f16_e32 v109, v93
	v_cvt_f32_f16_e32 v110, v94
	v_cvt_f32_f16_e32 v111, v95
	v_cvt_f32_f16_e32 v112, v96
	v_cvt_f32_f16_e32 v113, v97
	v_exp_f32_e32 v98, v98
	v_exp_f32_e32 v99, v99
	v_exp_f32_e32 v100, v100
	v_exp_f32_e32 v101, v101
	v_exp_f32_e32 v102, v102
	v_exp_f32_e32 v103, v103
	v_exp_f32_e32 v104, v104
	v_exp_f32_e32 v105, v105
	v_exp_f32_e32 v106, v106
	v_exp_f32_e32 v107, v107
	v_exp_f32_e32 v108, v108
	v_exp_f32_e32 v109, v109
	v_exp_f32_e32 v110, v110
	v_exp_f32_e32 v111, v111
	v_exp_f32_e32 v112, v112
	v_exp_f32_e32 v113, v113
	v_and_b32_e32 v82, 0xffff0000, v82
	v_and_b32_e32 v83, 0xffff0000, v83
	v_and_b32_e32 v84, 0xffff0000, v84
	v_and_b32_e32 v85, 0xffff0000, v85
	v_and_b32_e32 v86, 0xffff0000, v86
	v_and_b32_e32 v87, 0xffff0000, v87
	v_and_b32_e32 v88, 0xffff0000, v88
	v_and_b32_e32 v89, 0xffff0000, v89
	v_and_b32_e32 v90, 0xffff0000, v90
	v_and_b32_e32 v91, 0xffff0000, v91
	v_and_b32_e32 v92, 0xffff0000, v92
	v_and_b32_e32 v93, 0xffff0000, v93
	v_and_b32_e32 v94, 0xffff0000, v94
	v_and_b32_e32 v95, 0xffff0000, v95
	v_and_b32_e32 v96, 0xffff0000, v96
	v_and_b32_e32 v97, 0xffff0000, v97
	v_fmac_f32_e32 v82, v1, v98
	v_mul_f32_e32 v0, v0, v98
	v_fmac_f32_e32 v83, v82, v99
	v_mul_f32_e32 v0, v0, v99
	v_fmac_f32_e32 v84, v83, v100
	v_mul_f32_e32 v0, v0, v100
	v_fmac_f32_e32 v85, v84, v101
	v_mul_f32_e32 v0, v0, v101
	v_fmac_f32_e32 v86, v85, v102
	v_mul_f32_e32 v0, v0, v102
	v_fmac_f32_e32 v87, v86, v103
	v_mul_f32_e32 v0, v0, v103
	v_fmac_f32_e32 v88, v87, v104
	v_mul_f32_e32 v0, v0, v104
	v_fmac_f32_e32 v89, v88, v105
	v_mul_f32_e32 v0, v0, v105
	v_fmac_f32_e32 v90, v89, v106
	v_mul_f32_e32 v0, v0, v106
	v_fmac_f32_e32 v91, v90, v107
	v_mul_f32_e32 v0, v0, v107
	v_fmac_f32_e32 v92, v91, v108
	v_mul_f32_e32 v0, v0, v108
	v_fmac_f32_e32 v93, v92, v109
	v_mul_f32_e32 v0, v0, v109
	v_fmac_f32_e32 v94, v93, v110
	v_mul_f32_e32 v0, v0, v110
	v_fmac_f32_e32 v95, v94, v111
	v_mul_f32_e32 v0, v0, v111
	v_fmac_f32_e32 v96, v95, v112
	v_mul_f32_e32 v0, v0, v112
	v_fmac_f32_e32 v97, v96, v113
	v_mul_f32_e32 v0, v0, v113
	v_mov_b32_e32 v1, v97
	s_lshl_b32 s3, s3, 5
	s_or_b32 s14, s3, s87
	s_ashr_i32 s15, s14, 31
	s_lshl_b64 s[14:15], s[14:15], 13
	v_or_b32_sdwa v2, v162, s84 dst_sel:DWORD dst_unused:UNUSED_PAD src0_sel:BYTE_0 src1_sel:DWORD
	s_add_u32 s14, s0, s14
	s_addc_u32 s15, s1, s15
	v_lshlrev_b32_e32 v2, 3, v2
	global_store_dwordx2 v2, v[0:1], s[14:15]
	s_branch .LBB0_668

.Lscan2_body:
	ds_read2st64_b32 v[68:69], v2 offset1:4
	ds_read2st64_b32 v[70:71], v2 offset0:8 offset1:12
	ds_read2st64_b32 v[72:73], v2 offset0:16 offset1:20
	ds_read2st64_b32 v[74:75], v2 offset0:24 offset1:28
	ds_read2st64_b32 v[76:77], v2 offset0:32 offset1:36
	ds_read2st64_b32 v[78:79], v2 offset0:40 offset1:44
	ds_read2st64_b32 v[80:81], v2 offset0:48 offset1:52
	ds_read2st64_b32 v[82:83], v2 offset0:56 offset1:60
	s_waitcnt lgkmcnt(4)
	v_cvt_f32_f16_e32 v84, v68
	v_cvt_f32_f16_e32 v85, v69
	v_cvt_f32_f16_e32 v86, v70
	v_cvt_f32_f16_e32 v87, v71
	v_cvt_f32_f16_e32 v88, v72
	v_cvt_f32_f16_e32 v89, v73
	v_cvt_f32_f16_e32 v90, v74
	v_cvt_f32_f16_e32 v91, v75
	v_exp_f32_e32 v84, v84
	v_exp_f32_e32 v85, v85
	v_exp_f32_e32 v86, v86
	v_exp_f32_e32 v87, v87
	v_exp_f32_e32 v88, v88
	v_exp_f32_e32 v89, v89
	v_exp_f32_e32 v90, v90
	v_exp_f32_e32 v91, v91
	v_and_b32_e32 v68, 0xffff0000, v68
	v_and_b32_e32 v69, 0xffff0000, v69
	v_and_b32_e32 v70, 0xffff0000, v70
	v_and_b32_e32 v71, 0xffff0000, v71
	v_and_b32_e32 v72, 0xffff0000, v72
	v_and_b32_e32 v73, 0xffff0000, v73
	v_and_b32_e32 v74, 0xffff0000, v74
	v_and_b32_e32 v75, 0xffff0000, v75
	v_fmac_f32_e32 v68, v3, v84
	v_fmac_f32_e32 v69, v68, v85
	v_fmac_f32_e32 v70, v69, v86
	v_fmac_f32_e32 v71, v70, v87
	v_fmac_f32_e32 v72, v71, v88
	v_fmac_f32_e32 v73, v72, v89
	v_fmac_f32_e32 v74, v73, v90
	v_fmac_f32_e32 v75, v74, v91
	v_mov_b32_e32 v3, v75
	ds_write2st64_b32 v2, v68, v69 offset1:4
	ds_write2st64_b32 v2, v70, v71 offset0:8 offset1:12
	ds_write2st64_b32 v2, v72, v73 offset0:16 offset1:20
	ds_write2st64_b32 v2, v74, v75 offset0:24 offset1:28
	ds_read2st64_b32 v[68:69], v2 offset0:64 offset1:68
	ds_read2st64_b32 v[70:71], v2 offset0:72 offset1:76
	ds_read2st64_b32 v[72:73], v2 offset0:80 offset1:84
	ds_read2st64_b32 v[74:75], v2 offset0:88 offset1:92
	s_waitcnt lgkmcnt(8)
	v_cvt_f32_f16_e32 v84, v76
	v_cvt_f32_f16_e32 v85, v77
	v_cvt_f32_f16_e32 v86, v78
	v_cvt_f32_f16_e32 v87, v79
	v_cvt_f32_f16_e32 v88, v80
	v_cvt_f32_f16_e32 v89, v81
	v_cvt_f32_f16_e32 v90, v82
	v_cvt_f32_f16_e32 v91, v83
	v_exp_f32_e32 v84, v84
	v_exp_f32_e32 v85, v85
	v_exp_f32_e32 v86, v86
	v_exp_f32_e32 v87, v87
	v_exp_f32_e32 v88, v88
	v_exp_f32_e32 v89, v89
	v_exp_f32_e32 v90, v90
	v_exp_f32_e32 v91, v91
	v_and_b32_e32 v76, 0xffff0000, v76
	v_and_b32_e32 v77, 0xffff0000, v77
	v_and_b32_e32 v78, 0xffff0000, v78
	v_and_b32_e32 v79, 0xffff0000, v79
	v_and_b32_e32 v80, 0xffff0000, v80
	v_and_b32_e32 v81, 0xffff0000, v81
	v_and_b32_e32 v82, 0xffff0000, v82
	v_and_b32_e32 v83, 0xffff0000, v83
	v_fmac_f32_e32 v76, v3, v84
	v_fmac_f32_e32 v77, v76, v85
	v_fmac_f32_e32 v78, v77, v86
	v_fmac_f32_e32 v79, v78, v87
	v_fmac_f32_e32 v80, v79, v88
	v_fmac_f32_e32 v81, v80, v89
	v_fmac_f32_e32 v82, v81, v90
	v_fmac_f32_e32 v83, v82, v91
	v_mov_b32_e32 v3, v83
	ds_write2st64_b32 v2, v76, v77 offset0:32 offset1:36
	ds_write2st64_b32 v2, v78, v79 offset0:40 offset1:44
	ds_write2st64_b32 v2, v80, v81 offset0:48 offset1:52
	ds_write2st64_b32 v2, v82, v83 offset0:56 offset1:60
	ds_read2st64_b32 v[76:77], v2 offset0:96 offset1:100
	ds_read2st64_b32 v[78:79], v2 offset0:104 offset1:108
	ds_read2st64_b32 v[80:81], v2 offset0:112 offset1:116
	ds_read2st64_b32 v[82:83], v2 offset0:120 offset1:124
	s_waitcnt lgkmcnt(8)
	v_cvt_f32_f16_e32 v84, v68
	v_cvt_f32_f16_e32 v85, v69
	v_cvt_f32_f16_e32 v86, v70
	v_cvt_f32_f16_e32 v87, v71
	v_cvt_f32_f16_e32 v88, v72
	v_cvt_f32_f16_e32 v89, v73
	v_cvt_f32_f16_e32 v90, v74
	v_cvt_f32_f16_e32 v91, v75
	v_exp_f32_e32 v84, v84
	v_exp_f32_e32 v85, v85
	v_exp_f32_e32 v86, v86
	v_exp_f32_e32 v87, v87
	v_exp_f32_e32 v88, v88
	v_exp_f32_e32 v89, v89
	v_exp_f32_e32 v90, v90
	v_exp_f32_e32 v91, v91
	v_and_b32_e32 v68, 0xffff0000, v68
	v_and_b32_e32 v69, 0xffff0000, v69
	v_and_b32_e32 v70, 0xffff0000, v70
	v_and_b32_e32 v71, 0xffff0000, v71
	v_and_b32_e32 v72, 0xffff0000, v72
	v_and_b32_e32 v73, 0xffff0000, v73
	v_and_b32_e32 v74, 0xffff0000, v74
	v_and_b32_e32 v75, 0xffff0000, v75
	v_fmac_f32_e32 v68, v3, v84
	v_fmac_f32_e32 v69, v68, v85
	v_fmac_f32_e32 v70, v69, v86
	v_fmac_f32_e32 v71, v70, v87
	v_fmac_f32_e32 v72, v71, v88
	v_fmac_f32_e32 v73, v72, v89
	v_fmac_f32_e32 v74, v73, v90
	v_fmac_f32_e32 v75, v74, v91
	v_mov_b32_e32 v3, v75
	ds_write2st64_b32 v2, v68, v69 offset0:64 offset1:68
	ds_write2st64_b32 v2, v70, v71 offset0:72 offset1:76
	ds_write2st64_b32 v2, v72, v73 offset0:80 offset1:84
	ds_write2st64_b32 v2, v74, v75 offset0:88 offset1:92
	ds_read2st64_b32 v[68:69], v2 offset0:128 offset1:132
	ds_read2st64_b32 v[70:71], v2 offset0:136 offset1:140
	ds_read2st64_b32 v[72:73], v2 offset0:144 offset1:148
	ds_read2st64_b32 v[74:75], v2 offset0:152 offset1:156
	s_waitcnt lgkmcnt(8)
	v_cvt_f32_f16_e32 v84, v76
	v_cvt_f32_f16_e32 v85, v77
	v_cvt_f32_f16_e32 v86, v78
	v_cvt_f32_f16_e32 v87, v79
	v_cvt_f32_f16_e32 v88, v80
	v_cvt_f32_f16_e32 v89, v81
	v_cvt_f32_f16_e32 v90, v82
	v_cvt_f32_f16_e32 v91, v83
	v_exp_f32_e32 v84, v84
	v_exp_f32_e32 v85, v85
	v_exp_f32_e32 v86, v86
	v_exp_f32_e32 v87, v87
	v_exp_f32_e32 v88, v88
	v_exp_f32_e32 v89, v89
	v_exp_f32_e32 v90, v90
	v_exp_f32_e32 v91, v91
	v_and_b32_e32 v76, 0xffff0000, v76
	v_and_b32_e32 v77, 0xffff0000, v77
	v_and_b32_e32 v78, 0xffff0000, v78
	v_and_b32_e32 v79, 0xffff0000, v79
	v_and_b32_e32 v80, 0xffff0000, v80
	v_and_b32_e32 v81, 0xffff0000, v81
	v_and_b32_e32 v82, 0xffff0000, v82
	v_and_b32_e32 v83, 0xffff0000, v83
	v_fmac_f32_e32 v76, v3, v84
	v_fmac_f32_e32 v77, v76, v85
	v_fmac_f32_e32 v78, v77, v86
	v_fmac_f32_e32 v79, v78, v87
	v_fmac_f32_e32 v80, v79, v88
	v_fmac_f32_e32 v81, v80, v89
	v_fmac_f32_e32 v82, v81, v90
	v_fmac_f32_e32 v83, v82, v91
	v_mov_b32_e32 v3, v83
	ds_write2st64_b32 v2, v76, v77 offset0:96 offset1:100
	ds_write2st64_b32 v2, v78, v79 offset0:104 offset1:108
	ds_write2st64_b32 v2, v80, v81 offset0:112 offset1:116
	ds_write2st64_b32 v2, v82, v83 offset0:120 offset1:124
	ds_read2st64_b32 v[76:77], v2 offset0:160 offset1:164
	ds_read2st64_b32 v[78:79], v2 offset0:168 offset1:172
	ds_read2st64_b32 v[80:81], v2 offset0:176 offset1:180
	ds_read2st64_b32 v[82:83], v2 offset0:184 offset1:188
	s_waitcnt lgkmcnt(8)
	v_cvt_f32_f16_e32 v84, v68
	v_cvt_f32_f16_e32 v85, v69
	v_cvt_f32_f16_e32 v86, v70
	v_cvt_f32_f16_e32 v87, v71
	v_cvt_f32_f16_e32 v88, v72
	v_cvt_f32_f16_e32 v89, v73
	v_cvt_f32_f16_e32 v90, v74
	v_cvt_f32_f16_e32 v91, v75
	v_exp_f32_e32 v84, v84
	v_exp_f32_e32 v85, v85
	v_exp_f32_e32 v86, v86
	v_exp_f32_e32 v87, v87
	v_exp_f32_e32 v88, v88
	v_exp_f32_e32 v89, v89
	v_exp_f32_e32 v90, v90
	v_exp_f32_e32 v91, v91
	v_and_b32_e32 v68, 0xffff0000, v68
	v_and_b32_e32 v69, 0xffff0000, v69
	v_and_b32_e32 v70, 0xffff0000, v70
	v_and_b32_e32 v71, 0xffff0000, v71
	v_and_b32_e32 v72, 0xffff0000, v72
	v_and_b32_e32 v73, 0xffff0000, v73
	v_and_b32_e32 v74, 0xffff0000, v74
	v_and_b32_e32 v75, 0xffff0000, v75
	v_fmac_f32_e32 v68, v3, v84
	v_fmac_f32_e32 v69, v68, v85
	v_fmac_f32_e32 v70, v69, v86
	v_fmac_f32_e32 v71, v70, v87
	v_fmac_f32_e32 v72, v71, v88
	v_fmac_f32_e32 v73, v72, v89
	v_fmac_f32_e32 v74, v73, v90
	v_fmac_f32_e32 v75, v74, v91
	v_mov_b32_e32 v3, v75
	ds_write2st64_b32 v2, v68, v69 offset0:128 offset1:132
	ds_write2st64_b32 v2, v70, v71 offset0:136 offset1:140
	ds_write2st64_b32 v2, v72, v73 offset0:144 offset1:148
	ds_write2st64_b32 v2, v74, v75 offset0:152 offset1:156
	ds_read2st64_b32 v[68:69], v2 offset0:192 offset1:196
	ds_read2st64_b32 v[70:71], v2 offset0:200 offset1:204
	ds_read2st64_b32 v[72:73], v2 offset0:208 offset1:212
	ds_read2st64_b32 v[74:75], v2 offset0:216 offset1:220
	s_waitcnt lgkmcnt(8)
	v_cvt_f32_f16_e32 v84, v76
	v_cvt_f32_f16_e32 v85, v77
	v_cvt_f32_f16_e32 v86, v78
	v_cvt_f32_f16_e32 v87, v79
	v_cvt_f32_f16_e32 v88, v80
	v_cvt_f32_f16_e32 v89, v81
	v_cvt_f32_f16_e32 v90, v82
	v_cvt_f32_f16_e32 v91, v83
	v_exp_f32_e32 v84, v84
	v_exp_f32_e32 v85, v85
	v_exp_f32_e32 v86, v86
	v_exp_f32_e32 v87, v87
	v_exp_f32_e32 v88, v88
	v_exp_f32_e32 v89, v89
	v_exp_f32_e32 v90, v90
	v_exp_f32_e32 v91, v91
	v_and_b32_e32 v76, 0xffff0000, v76
	v_and_b32_e32 v77, 0xffff0000, v77
	v_and_b32_e32 v78, 0xffff0000, v78
	v_and_b32_e32 v79, 0xffff0000, v79
	v_and_b32_e32 v80, 0xffff0000, v80
	v_and_b32_e32 v81, 0xffff0000, v81
	v_and_b32_e32 v82, 0xffff0000, v82
	v_and_b32_e32 v83, 0xffff0000, v83
	v_fmac_f32_e32 v76, v3, v84
	v_fmac_f32_e32 v77, v76, v85
	v_fmac_f32_e32 v78, v77, v86
	v_fmac_f32_e32 v79, v78, v87
	v_fmac_f32_e32 v80, v79, v88
	v_fmac_f32_e32 v81, v80, v89
	v_fmac_f32_e32 v82, v81, v90
	v_fmac_f32_e32 v83, v82, v91
	v_mov_b32_e32 v3, v83
	ds_write2st64_b32 v2, v76, v77 offset0:160 offset1:164
	ds_write2st64_b32 v2, v78, v79 offset0:168 offset1:172
	ds_write2st64_b32 v2, v80, v81 offset0:176 offset1:180
	ds_write2st64_b32 v2, v82, v83 offset0:184 offset1:188
	ds_read2st64_b32 v[76:77], v2 offset0:224 offset1:228
	ds_read2st64_b32 v[78:79], v2 offset0:232 offset1:236
	ds_read2st64_b32 v[80:81], v2 offset0:240 offset1:244
	ds_read2st64_b32 v[82:83], v2 offset0:248 offset1:252
	s_waitcnt lgkmcnt(8)
	v_cvt_f32_f16_e32 v84, v68
	v_cvt_f32_f16_e32 v85, v69
	v_cvt_f32_f16_e32 v86, v70
	v_cvt_f32_f16_e32 v87, v71
	v_cvt_f32_f16_e32 v88, v72
	v_cvt_f32_f16_e32 v89, v73
	v_cvt_f32_f16_e32 v90, v74
	v_cvt_f32_f16_e32 v91, v75
	v_exp_f32_e32 v84, v84
	v_exp_f32_e32 v85, v85
	v_exp_f32_e32 v86, v86
	v_exp_f32_e32 v87, v87
	v_exp_f32_e32 v88, v88
	v_exp_f32_e32 v89, v89
	v_exp_f32_e32 v90, v90
	v_exp_f32_e32 v91, v91
	v_and_b32_e32 v68, 0xffff0000, v68
	v_and_b32_e32 v69, 0xffff0000, v69
	v_and_b32_e32 v70, 0xffff0000, v70
	v_and_b32_e32 v71, 0xffff0000, v71
	v_and_b32_e32 v72, 0xffff0000, v72
	v_and_b32_e32 v73, 0xffff0000, v73
	v_and_b32_e32 v74, 0xffff0000, v74
	v_and_b32_e32 v75, 0xffff0000, v75
	v_fmac_f32_e32 v68, v3, v84
	v_fmac_f32_e32 v69, v68, v85
	v_fmac_f32_e32 v70, v69, v86
	v_fmac_f32_e32 v71, v70, v87
	v_fmac_f32_e32 v72, v71, v88
	v_fmac_f32_e32 v73, v72, v89
	v_fmac_f32_e32 v74, v73, v90
	v_fmac_f32_e32 v75, v74, v91
	v_mov_b32_e32 v3, v75
	ds_write2st64_b32 v2, v68, v69 offset0:192 offset1:196
	ds_write2st64_b32 v2, v70, v71 offset0:200 offset1:204
	ds_write2st64_b32 v2, v72, v73 offset0:208 offset1:212
	ds_write2st64_b32 v2, v74, v75 offset0:216 offset1:220
	s_waitcnt lgkmcnt(4)
	v_cvt_f32_f16_e32 v84, v76
	v_cvt_f32_f16_e32 v85, v77
	v_cvt_f32_f16_e32 v86, v78
	v_cvt_f32_f16_e32 v87, v79
	v_cvt_f32_f16_e32 v88, v80
	v_cvt_f32_f16_e32 v89, v81
	v_cvt_f32_f16_e32 v90, v82
	v_cvt_f32_f16_e32 v91, v83
	v_exp_f32_e32 v84, v84
	v_exp_f32_e32 v85, v85
	v_exp_f32_e32 v86, v86
	v_exp_f32_e32 v87, v87
	v_exp_f32_e32 v88, v88
	v_exp_f32_e32 v89, v89
	v_exp_f32_e32 v90, v90
	v_exp_f32_e32 v91, v91
	v_and_b32_e32 v76, 0xffff0000, v76
	v_and_b32_e32 v77, 0xffff0000, v77
	v_and_b32_e32 v78, 0xffff0000, v78
	v_and_b32_e32 v79, 0xffff0000, v79
	v_and_b32_e32 v80, 0xffff0000, v80
	v_and_b32_e32 v81, 0xffff0000, v81
	v_and_b32_e32 v82, 0xffff0000, v82
	v_and_b32_e32 v83, 0xffff0000, v83
	v_fmac_f32_e32 v76, v3, v84
	v_fmac_f32_e32 v77, v76, v85
	v_fmac_f32_e32 v78, v77, v86
	v_fmac_f32_e32 v79, v78, v87
	v_fmac_f32_e32 v80, v79, v88
	v_fmac_f32_e32 v81, v80, v89
	v_fmac_f32_e32 v82, v81, v90
	v_fmac_f32_e32 v83, v82, v91
	v_mov_b32_e32 v3, v83
	ds_write2st64_b32 v2, v76, v77 offset0:224 offset1:228
	ds_write2st64_b32 v2, v78, v79 offset0:232 offset1:236
	ds_write2st64_b32 v2, v80, v81 offset0:240 offset1:244
	ds_write2st64_b32 v2, v82, v83 offset0:248 offset1:252
	s_and_b64 vcc, exec, s[38:39]
	s_cbranch_vccz .LBB0_743
	s_load_dwordx2 s[16:17], s[6:7], 0xf8
	s_add_i32 s18, s54, s1
	s_ashr_i32 s19, s18, 31
	s_lshl_b64 s[18:19], s[18:19], 12
	s_waitcnt lgkmcnt(0)
	s_add_u32 s16, s16, s18
	s_addc_u32 s17, s17, s19
	v_lshl_add_u64 v[0:1], v[0:1], 2, s[16:17]
	v_add_co_u32_e32 v0, vcc, 0x4400000, v0
	s_nop 1
	v_addc_co_u32_e32 v1, vcc, 0, v1, vcc
	global_store_dword v[0:1], v3, off
	s_branch .LBB0_743
